# attention item epilogue rewritten by hand: per-head RMSNorm cross-lane sums via DPP + v_permlane16_swap batched over 4 rows (was 9 serialized ds_bpermute round trips per row), stores at the end
# speedup vs baseline: 1.0038x; 1.0038x over previous
; __device__ __forceinline__ unsigned cvt_pk_bf16(float lo, float hi) { unsigned r; asm volatile("v_cvt_pk_bf16_f32 %0, %1, %2" : "=v"(r) : "v"(lo), "v"(hi)); return r; }
; __device__ __forceinline__ int crow(int r, int hi) { return (r & 3) + 8 * (r >> 2) + 4 * hi; }
; __device__ __forceinline__ void block(const BlockRef& cur, const int j0, const int NT, const int split, const SplitRef sp, lptr lds, int tid) {
;     ...
;     if (hi == 0) li_l[r32] = l_reg; asm volatile("s_waitcnt lgkmcnt(0)" ::: "memory");
;     bf16_t* Ow = cur.O + (size_t)(wid * QBLK) * DM;
; #pragma unroll
;     for (int r = 0; r < 16; ++r) { const int orow = crow(r, hi); const float rli = __builtin_amdgcn_rcpf(li_l[orow]);
;         float v0 = o[0][r] * rli, v1 = o[1][r] * rli, v2 = o[2][r] * rli, v3 = o[3][r] * rli;
;         float ss = (v0 * v0 + v1 * v1) + (v2 * v2 + v3 * v3);
;         ss += __shfl_xor(ss, 1); ss += __shfl_xor(ss, 2); ss += __shfl_xor(ss, 4); ss += __shfl_xor(ss, 8); ss += __shfl_xor(ss, 16);
;         const float rs = rsqrtf(ss * (1.0f / 128.0f) + EPS);
;         v0 *= rs; v1 *= rs; v2 *= rs; v3 *= rs;
;         const float n0 = __shfl_xor(v0, 1), n1 = __shfl_xor(v1, 1), n2 = __shfl_xor(v2, 1), n3 = __shfl_xor(v3, 1);
;         if ((r32 & 1) == 0) { bf16_t* op = Ow + (size_t)orow * DM + r32;
;             *(unsigned*)(op) = cvt_pk_bf16(v0, n0); *(unsigned*)(op + 32) = cvt_pk_bf16(v1, n1); *(unsigned*)(op + 64) = cvt_pk_bf16(v2, n2); *(unsigned*)(op + 96) = cvt_pk_bf16(v3, n3); } }
.LBB0_916:
	v_cmp_gt_u32_e32 vcc, 32, v216
	s_and_saveexec_b64 s[4:5], vcc
	v_lshl_add_u32 v1, v219, 2, s1
	ds_write_b32 v1, v220
	s_or_b64 exec, exec, s[4:5]
	s_waitcnt lgkmcnt(0)
	s_lshl_b32 s1, s96, 21
	s_and_b32 s1, s1, 0x3000000
	v_readlane_b32 s4, v255, 13
	s_add_u32 s1, s4, s1
	v_readlane_b32 s4, v255, 14
	s_addc_u32 s4, s4, 0
	s_lshl_b32 s5, s96, 8
	s_and_b32 s5, s5, 0x700
	s_add_u32 s1, s1, s5
	s_addc_u32 s6, s4, 0
	s_lshl_b64 s[4:5], s[74:75], 20
	s_add_u32 s4, s1, s4
	s_addc_u32 s5, s6, s5
	s_ashr_i32 s1, s0, 31
	s_lshl_b64 s[0:1], s[0:1], 12
	s_add_u32 s4, s4, s0
	s_addc_u32 s5, s5, s1
	v_and_b32_e32 v1, 1, v174
	v_lshlrev_b32_e32 v162, 1, v219
	v_cmp_eq_u32_e32 vcc, 0, v1
	v_lshl_add_u32 v162, v217, 14, v162
	ds_read_b32 v66, v218
	ds_read_b32 v67, v218 offset:4
	ds_read_b32 v68, v218 offset:8
	ds_read_b32 v69, v218 offset:12
	s_waitcnt lgkmcnt(0)
	v_rcp_f32_e32 v66, v66
	v_rcp_f32_e32 v67, v67
	v_rcp_f32_e32 v68, v68
	v_rcp_f32_e32 v69, v69
	v_pk_mul_f32 v[50:51], v[50:51], v[66:67]
	v_pk_mul_f32 v[34:35], v[34:35], v[66:67]
	v_pk_mul_f32 v[18:19], v[18:19], v[66:67]
	v_pk_mul_f32 v[2:3], v[2:3], v[66:67]
	v_pk_mul_f32 v[52:53], v[52:53], v[68:69]
	v_pk_mul_f32 v[36:37], v[36:37], v[68:69]
	v_pk_mul_f32 v[20:21], v[20:21], v[68:69]
	v_pk_mul_f32 v[4:5], v[4:5], v[68:69]
	v_pk_mul_f32 v[70:71], v[50:51], v[50:51]
	v_pk_mul_f32 v[72:73], v[52:53], v[52:53]
	v_pk_fma_f32 v[70:71], v[34:35], v[34:35], v[70:71]
	v_pk_fma_f32 v[72:73], v[36:37], v[36:37], v[72:73]
	v_pk_fma_f32 v[70:71], v[18:19], v[18:19], v[70:71]
	v_pk_fma_f32 v[72:73], v[20:21], v[20:21], v[72:73]
	v_pk_fma_f32 v[70:71], v[2:3], v[2:3], v[70:71]
	v_pk_fma_f32 v[72:73], v[4:5], v[4:5], v[72:73]
	s_nop 1
	v_add_f32_dpp v70, v70, v70 quad_perm:[1,0,3,2] row_mask:0xf bank_mask:0xf
	v_add_f32_dpp v71, v71, v71 quad_perm:[1,0,3,2] row_mask:0xf bank_mask:0xf
	v_add_f32_dpp v72, v72, v72 quad_perm:[1,0,3,2] row_mask:0xf bank_mask:0xf
	v_add_f32_dpp v73, v73, v73 quad_perm:[1,0,3,2] row_mask:0xf bank_mask:0xf
	v_add_f32_dpp v70, v70, v70 quad_perm:[2,3,0,1] row_mask:0xf bank_mask:0xf
	v_add_f32_dpp v71, v71, v71 quad_perm:[2,3,0,1] row_mask:0xf bank_mask:0xf
	v_add_f32_dpp v72, v72, v72 quad_perm:[2,3,0,1] row_mask:0xf bank_mask:0xf
	v_add_f32_dpp v73, v73, v73 quad_perm:[2,3,0,1] row_mask:0xf bank_mask:0xf
	v_add_f32_dpp v70, v70, v70 row_half_mirror row_mask:0xf bank_mask:0xf
	v_add_f32_dpp v71, v71, v71 row_half_mirror row_mask:0xf bank_mask:0xf
	v_add_f32_dpp v72, v72, v72 row_half_mirror row_mask:0xf bank_mask:0xf
	v_add_f32_dpp v73, v73, v73 row_half_mirror row_mask:0xf bank_mask:0xf
	v_add_f32_dpp v70, v70, v70 row_mirror row_mask:0xf bank_mask:0xf
	v_add_f32_dpp v71, v71, v71 row_mirror row_mask:0xf bank_mask:0xf
	v_add_f32_dpp v72, v72, v72 row_mirror row_mask:0xf bank_mask:0xf
	v_add_f32_dpp v73, v73, v73 row_mirror row_mask:0xf bank_mask:0xf
	v_mov_b32_e32 v74, v70
	v_mov_b32_e32 v75, v71
	v_mov_b32_e32 v76, v72
	v_mov_b32_e32 v77, v73
	v_permlane16_swap_b32_e32 v70, v74
	v_permlane16_swap_b32_e32 v71, v75
	v_permlane16_swap_b32_e32 v72, v76
	v_permlane16_swap_b32_e32 v73, v77
	v_add_f32_e32 v70, v70, v74
	v_add_f32_e32 v71, v71, v75
	v_add_f32_e32 v72, v72, v76
	v_add_f32_e32 v73, v73, v77
	v_fmamk_f32 v70, v70, 0x3c000000, v192
	v_fmamk_f32 v71, v71, 0x3c000000, v192
	v_fmamk_f32 v72, v72, 0x3c000000, v192
	v_fmamk_f32 v73, v73, 0x3c000000, v192
	v_rsq_f32_e32 v70, v70
	v_rsq_f32_e32 v71, v71
	v_rsq_f32_e32 v72, v72
	v_rsq_f32_e32 v73, v73
	s_nop 0
	v_pk_mul_f32 v[50:51], v[50:51], v[70:71]
	v_pk_mul_f32 v[34:35], v[34:35], v[70:71]
	v_pk_mul_f32 v[18:19], v[18:19], v[70:71]
	v_pk_mul_f32 v[2:3], v[2:3], v[70:71]
	v_pk_mul_f32 v[52:53], v[52:53], v[72:73]
	v_pk_mul_f32 v[36:37], v[36:37], v[72:73]
	v_pk_mul_f32 v[20:21], v[20:21], v[72:73]
	v_pk_mul_f32 v[4:5], v[4:5], v[72:73]
	s_nop 0
	v_mov_b32_dpp v74, v50 quad_perm:[1,0,3,2] row_mask:0xf bank_mask:0xf
	v_mov_b32_dpp v75, v34 quad_perm:[1,0,3,2] row_mask:0xf bank_mask:0xf
	v_mov_b32_dpp v76, v18 quad_perm:[1,0,3,2] row_mask:0xf bank_mask:0xf
	v_mov_b32_dpp v77, v2 quad_perm:[1,0,3,2] row_mask:0xf bank_mask:0xf
	v_cvt_pk_bf16_f32 v50, v50, v74
	v_cvt_pk_bf16_f32 v34, v34, v75
	v_cvt_pk_bf16_f32 v18, v18, v76
	v_cvt_pk_bf16_f32 v2, v2, v77
	v_mov_b32_dpp v74, v51 quad_perm:[1,0,3,2] row_mask:0xf bank_mask:0xf
	v_mov_b32_dpp v75, v35 quad_perm:[1,0,3,2] row_mask:0xf bank_mask:0xf
	v_mov_b32_dpp v76, v19 quad_perm:[1,0,3,2] row_mask:0xf bank_mask:0xf
	v_mov_b32_dpp v77, v3 quad_perm:[1,0,3,2] row_mask:0xf bank_mask:0xf
	v_cvt_pk_bf16_f32 v51, v51, v74
	v_cvt_pk_bf16_f32 v35, v35, v75
	v_cvt_pk_bf16_f32 v19, v19, v76
	v_cvt_pk_bf16_f32 v3, v3, v77
	v_mov_b32_dpp v74, v52 quad_perm:[1,0,3,2] row_mask:0xf bank_mask:0xf
	v_mov_b32_dpp v75, v36 quad_perm:[1,0,3,2] row_mask:0xf bank_mask:0xf
	v_mov_b32_dpp v76, v20 quad_perm:[1,0,3,2] row_mask:0xf bank_mask:0xf
	v_mov_b32_dpp v77, v4 quad_perm:[1,0,3,2] row_mask:0xf bank_mask:0xf
	v_cvt_pk_bf16_f32 v52, v52, v74
	v_cvt_pk_bf16_f32 v36, v36, v75
	v_cvt_pk_bf16_f32 v20, v20, v76
	v_cvt_pk_bf16_f32 v4, v4, v77
	v_mov_b32_dpp v74, v53 quad_perm:[1,0,3,2] row_mask:0xf bank_mask:0xf
	v_mov_b32_dpp v75, v37 quad_perm:[1,0,3,2] row_mask:0xf bank_mask:0xf
	v_mov_b32_dpp v76, v21 quad_perm:[1,0,3,2] row_mask:0xf bank_mask:0xf
	v_mov_b32_dpp v77, v5 quad_perm:[1,0,3,2] row_mask:0xf bank_mask:0xf
	v_cvt_pk_bf16_f32 v53, v53, v74
	v_cvt_pk_bf16_f32 v37, v37, v75
	v_cvt_pk_bf16_f32 v21, v21, v76
	v_cvt_pk_bf16_f32 v5, v5, v77
	ds_read_b32 v66, v218 offset:32
	ds_read_b32 v67, v218 offset:36
	ds_read_b32 v68, v218 offset:40
	ds_read_b32 v69, v218 offset:44
	s_waitcnt lgkmcnt(0)
; __device__ __forceinline__ unsigned cvt_pk_bf16(float lo, float hi) { unsigned r; asm volatile("v_cvt_pk_bf16_f32 %0, %1, %2" : "=v"(r) : "v"(lo), "v"(hi)); return r; }
; __device__ __forceinline__ int crow(int r, int hi) { return (r & 3) + 8 * (r >> 2) + 4 * hi; }
; __device__ __forceinline__ void block(const BlockRef& cur, const int j0, const int NT, const int split, const SplitRef sp, lptr lds, int tid) {
;     ...
;     if (hi == 0) li_l[r32] = l_reg; asm volatile("s_waitcnt lgkmcnt(0)" ::: "memory");
;     bf16_t* Ow = cur.O + (size_t)(wid * QBLK) * DM;
; #pragma unroll
;     for (int r = 0; r < 16; ++r) { const int orow = crow(r, hi); const float rli = __builtin_amdgcn_rcpf(li_l[orow]);
;         float v0 = o[0][r] * rli, v1 = o[1][r] * rli, v2 = o[2][r] * rli, v3 = o[3][r] * rli;
;         float ss = (v0 * v0 + v1 * v1) + (v2 * v2 + v3 * v3);
;         ss += __shfl_xor(ss, 1); ss += __shfl_xor(ss, 2); ss += __shfl_xor(ss, 4); ss += __shfl_xor(ss, 8); ss += __shfl_xor(ss, 16);
;         const float rs = rsqrtf(ss * (1.0f / 128.0f) + EPS);
;         v0 *= rs; v1 *= rs; v2 *= rs; v3 *= rs;
;         const float n0 = __shfl_xor(v0, 1), n1 = __shfl_xor(v1, 1), n2 = __shfl_xor(v2, 1), n3 = __shfl_xor(v3, 1);
;         if ((r32 & 1) == 0) { bf16_t* op = Ow + (size_t)orow * DM + r32;
;             *(unsigned*)(op) = cvt_pk_bf16(v0, n0); *(unsigned*)(op + 32) = cvt_pk_bf16(v1, n1); *(unsigned*)(op + 64) = cvt_pk_bf16(v2, n2); *(unsigned*)(op + 96) = cvt_pk_bf16(v3, n3); } }
	v_rcp_f32_e32 v66, v66
	v_rcp_f32_e32 v67, v67
	v_rcp_f32_e32 v68, v68
	v_rcp_f32_e32 v69, v69
	v_pk_mul_f32 v[54:55], v[54:55], v[66:67]
	v_pk_mul_f32 v[38:39], v[38:39], v[66:67]
	v_pk_mul_f32 v[22:23], v[22:23], v[66:67]
	v_pk_mul_f32 v[6:7], v[6:7], v[66:67]
	v_pk_mul_f32 v[56:57], v[56:57], v[68:69]
	v_pk_mul_f32 v[40:41], v[40:41], v[68:69]
	v_pk_mul_f32 v[24:25], v[24:25], v[68:69]
	v_pk_mul_f32 v[8:9], v[8:9], v[68:69]
	v_pk_mul_f32 v[70:71], v[54:55], v[54:55]
	v_pk_mul_f32 v[72:73], v[56:57], v[56:57]
	v_pk_fma_f32 v[70:71], v[38:39], v[38:39], v[70:71]
	v_pk_fma_f32 v[72:73], v[40:41], v[40:41], v[72:73]
	v_pk_fma_f32 v[70:71], v[22:23], v[22:23], v[70:71]
	v_pk_fma_f32 v[72:73], v[24:25], v[24:25], v[72:73]
	v_pk_fma_f32 v[70:71], v[6:7], v[6:7], v[70:71]
	v_pk_fma_f32 v[72:73], v[8:9], v[8:9], v[72:73]
	s_nop 1
	v_add_f32_dpp v70, v70, v70 quad_perm:[1,0,3,2] row_mask:0xf bank_mask:0xf
	v_add_f32_dpp v71, v71, v71 quad_perm:[1,0,3,2] row_mask:0xf bank_mask:0xf
	v_add_f32_dpp v72, v72, v72 quad_perm:[1,0,3,2] row_mask:0xf bank_mask:0xf
	v_add_f32_dpp v73, v73, v73 quad_perm:[1,0,3,2] row_mask:0xf bank_mask:0xf
	v_add_f32_dpp v70, v70, v70 quad_perm:[2,3,0,1] row_mask:0xf bank_mask:0xf
	v_add_f32_dpp v71, v71, v71 quad_perm:[2,3,0,1] row_mask:0xf bank_mask:0xf
	v_add_f32_dpp v72, v72, v72 quad_perm:[2,3,0,1] row_mask:0xf bank_mask:0xf
	v_add_f32_dpp v73, v73, v73 quad_perm:[2,3,0,1] row_mask:0xf bank_mask:0xf
	v_add_f32_dpp v70, v70, v70 row_half_mirror row_mask:0xf bank_mask:0xf
	v_add_f32_dpp v71, v71, v71 row_half_mirror row_mask:0xf bank_mask:0xf
	v_add_f32_dpp v72, v72, v72 row_half_mirror row_mask:0xf bank_mask:0xf
	v_add_f32_dpp v73, v73, v73 row_half_mirror row_mask:0xf bank_mask:0xf
	v_add_f32_dpp v70, v70, v70 row_mirror row_mask:0xf bank_mask:0xf
	v_add_f32_dpp v71, v71, v71 row_mirror row_mask:0xf bank_mask:0xf
	v_add_f32_dpp v72, v72, v72 row_mirror row_mask:0xf bank_mask:0xf
	v_add_f32_dpp v73, v73, v73 row_mirror row_mask:0xf bank_mask:0xf
	v_mov_b32_e32 v74, v70
	v_mov_b32_e32 v75, v71
	v_mov_b32_e32 v76, v72
	v_mov_b32_e32 v77, v73
	v_permlane16_swap_b32_e32 v70, v74
	v_permlane16_swap_b32_e32 v71, v75
	v_permlane16_swap_b32_e32 v72, v76
	v_permlane16_swap_b32_e32 v73, v77
	v_add_f32_e32 v70, v70, v74
	v_add_f32_e32 v71, v71, v75
	v_add_f32_e32 v72, v72, v76
	v_add_f32_e32 v73, v73, v77
	v_fmamk_f32 v70, v70, 0x3c000000, v192
	v_fmamk_f32 v71, v71, 0x3c000000, v192
	v_fmamk_f32 v72, v72, 0x3c000000, v192
	v_fmamk_f32 v73, v73, 0x3c000000, v192
	v_rsq_f32_e32 v70, v70
	v_rsq_f32_e32 v71, v71
	v_rsq_f32_e32 v72, v72
	v_rsq_f32_e32 v73, v73
	s_nop 0
	v_pk_mul_f32 v[54:55], v[54:55], v[70:71]
	v_pk_mul_f32 v[38:39], v[38:39], v[70:71]
	v_pk_mul_f32 v[22:23], v[22:23], v[70:71]
	v_pk_mul_f32 v[6:7], v[6:7], v[70:71]
	v_pk_mul_f32 v[56:57], v[56:57], v[72:73]
	v_pk_mul_f32 v[40:41], v[40:41], v[72:73]
	v_pk_mul_f32 v[24:25], v[24:25], v[72:73]
	v_pk_mul_f32 v[8:9], v[8:9], v[72:73]
	s_nop 0
	v_mov_b32_dpp v74, v54 quad_perm:[1,0,3,2] row_mask:0xf bank_mask:0xf
	v_mov_b32_dpp v75, v38 quad_perm:[1,0,3,2] row_mask:0xf bank_mask:0xf
	v_mov_b32_dpp v76, v22 quad_perm:[1,0,3,2] row_mask:0xf bank_mask:0xf
	v_mov_b32_dpp v77, v6 quad_perm:[1,0,3,2] row_mask:0xf bank_mask:0xf
	v_cvt_pk_bf16_f32 v54, v54, v74
	v_cvt_pk_bf16_f32 v38, v38, v75
	v_cvt_pk_bf16_f32 v22, v22, v76
	v_cvt_pk_bf16_f32 v6, v6, v77
	v_mov_b32_dpp v74, v55 quad_perm:[1,0,3,2] row_mask:0xf bank_mask:0xf
	v_mov_b32_dpp v75, v39 quad_perm:[1,0,3,2] row_mask:0xf bank_mask:0xf
	v_mov_b32_dpp v76, v23 quad_perm:[1,0,3,2] row_mask:0xf bank_mask:0xf
	v_mov_b32_dpp v77, v7 quad_perm:[1,0,3,2] row_mask:0xf bank_mask:0xf
	v_cvt_pk_bf16_f32 v55, v55, v74
	v_cvt_pk_bf16_f32 v39, v39, v75
	v_cvt_pk_bf16_f32 v23, v23, v76
	v_cvt_pk_bf16_f32 v7, v7, v77
	v_mov_b32_dpp v74, v56 quad_perm:[1,0,3,2] row_mask:0xf bank_mask:0xf
	v_mov_b32_dpp v75, v40 quad_perm:[1,0,3,2] row_mask:0xf bank_mask:0xf
	v_mov_b32_dpp v76, v24 quad_perm:[1,0,3,2] row_mask:0xf bank_mask:0xf
	v_mov_b32_dpp v77, v8 quad_perm:[1,0,3,2] row_mask:0xf bank_mask:0xf
	v_cvt_pk_bf16_f32 v56, v56, v74
	v_cvt_pk_bf16_f32 v40, v40, v75
	v_cvt_pk_bf16_f32 v24, v24, v76
	v_cvt_pk_bf16_f32 v8, v8, v77
	v_mov_b32_dpp v74, v57 quad_perm:[1,0,3,2] row_mask:0xf bank_mask:0xf
	v_mov_b32_dpp v75, v41 quad_perm:[1,0,3,2] row_mask:0xf bank_mask:0xf
	v_mov_b32_dpp v76, v25 quad_perm:[1,0,3,2] row_mask:0xf bank_mask:0xf
	v_mov_b32_dpp v77, v9 quad_perm:[1,0,3,2] row_mask:0xf bank_mask:0xf
	v_cvt_pk_bf16_f32 v57, v57, v74
	v_cvt_pk_bf16_f32 v41, v41, v75
	v_cvt_pk_bf16_f32 v25, v25, v76
	v_cvt_pk_bf16_f32 v9, v9, v77
	ds_read_b32 v66, v218 offset:64
	ds_read_b32 v67, v218 offset:68
	ds_read_b32 v68, v218 offset:72
	ds_read_b32 v69, v218 offset:76
	s_waitcnt lgkmcnt(0)
; __device__ __forceinline__ unsigned cvt_pk_bf16(float lo, float hi) { unsigned r; asm volatile("v_cvt_pk_bf16_f32 %0, %1, %2" : "=v"(r) : "v"(lo), "v"(hi)); return r; }
; __device__ __forceinline__ int crow(int r, int hi) { return (r & 3) + 8 * (r >> 2) + 4 * hi; }
; __device__ __forceinline__ void block(const BlockRef& cur, const int j0, const int NT, const int split, const SplitRef sp, lptr lds, int tid) {
;     ...
;     if (hi == 0) li_l[r32] = l_reg; asm volatile("s_waitcnt lgkmcnt(0)" ::: "memory");
;     bf16_t* Ow = cur.O + (size_t)(wid * QBLK) * DM;
; #pragma unroll
;     for (int r = 0; r < 16; ++r) { const int orow = crow(r, hi); const float rli = __builtin_amdgcn_rcpf(li_l[orow]);
;         float v0 = o[0][r] * rli, v1 = o[1][r] * rli, v2 = o[2][r] * rli, v3 = o[3][r] * rli;
;         float ss = (v0 * v0 + v1 * v1) + (v2 * v2 + v3 * v3);
;         ss += __shfl_xor(ss, 1); ss += __shfl_xor(ss, 2); ss += __shfl_xor(ss, 4); ss += __shfl_xor(ss, 8); ss += __shfl_xor(ss, 16);
;         const float rs = rsqrtf(ss * (1.0f / 128.0f) + EPS);
;         v0 *= rs; v1 *= rs; v2 *= rs; v3 *= rs;
;         const float n0 = __shfl_xor(v0, 1), n1 = __shfl_xor(v1, 1), n2 = __shfl_xor(v2, 1), n3 = __shfl_xor(v3, 1);
;         if ((r32 & 1) == 0) { bf16_t* op = Ow + (size_t)orow * DM + r32;
;             *(unsigned*)(op) = cvt_pk_bf16(v0, n0); *(unsigned*)(op + 32) = cvt_pk_bf16(v1, n1); *(unsigned*)(op + 64) = cvt_pk_bf16(v2, n2); *(unsigned*)(op + 96) = cvt_pk_bf16(v3, n3); } }
	v_rcp_f32_e32 v66, v66
	v_rcp_f32_e32 v67, v67
	v_rcp_f32_e32 v68, v68
	v_rcp_f32_e32 v69, v69
	v_pk_mul_f32 v[58:59], v[58:59], v[66:67]
	v_pk_mul_f32 v[42:43], v[42:43], v[66:67]
	v_pk_mul_f32 v[26:27], v[26:27], v[66:67]
	v_pk_mul_f32 v[10:11], v[10:11], v[66:67]
	v_pk_mul_f32 v[60:61], v[60:61], v[68:69]
	v_pk_mul_f32 v[44:45], v[44:45], v[68:69]
	v_pk_mul_f32 v[28:29], v[28:29], v[68:69]
	v_pk_mul_f32 v[12:13], v[12:13], v[68:69]
	v_pk_mul_f32 v[70:71], v[58:59], v[58:59]
	v_pk_mul_f32 v[72:73], v[60:61], v[60:61]
	v_pk_fma_f32 v[70:71], v[42:43], v[42:43], v[70:71]
	v_pk_fma_f32 v[72:73], v[44:45], v[44:45], v[72:73]
	v_pk_fma_f32 v[70:71], v[26:27], v[26:27], v[70:71]
	v_pk_fma_f32 v[72:73], v[28:29], v[28:29], v[72:73]
	v_pk_fma_f32 v[70:71], v[10:11], v[10:11], v[70:71]
	v_pk_fma_f32 v[72:73], v[12:13], v[12:13], v[72:73]
	s_nop 1
	v_add_f32_dpp v70, v70, v70 quad_perm:[1,0,3,2] row_mask:0xf bank_mask:0xf
	v_add_f32_dpp v71, v71, v71 quad_perm:[1,0,3,2] row_mask:0xf bank_mask:0xf
	v_add_f32_dpp v72, v72, v72 quad_perm:[1,0,3,2] row_mask:0xf bank_mask:0xf
	v_add_f32_dpp v73, v73, v73 quad_perm:[1,0,3,2] row_mask:0xf bank_mask:0xf
	v_add_f32_dpp v70, v70, v70 quad_perm:[2,3,0,1] row_mask:0xf bank_mask:0xf
	v_add_f32_dpp v71, v71, v71 quad_perm:[2,3,0,1] row_mask:0xf bank_mask:0xf
	v_add_f32_dpp v72, v72, v72 quad_perm:[2,3,0,1] row_mask:0xf bank_mask:0xf
	v_add_f32_dpp v73, v73, v73 quad_perm:[2,3,0,1] row_mask:0xf bank_mask:0xf
	v_add_f32_dpp v70, v70, v70 row_half_mirror row_mask:0xf bank_mask:0xf
	v_add_f32_dpp v71, v71, v71 row_half_mirror row_mask:0xf bank_mask:0xf
	v_add_f32_dpp v72, v72, v72 row_half_mirror row_mask:0xf bank_mask:0xf
	v_add_f32_dpp v73, v73, v73 row_half_mirror row_mask:0xf bank_mask:0xf
	v_add_f32_dpp v70, v70, v70 row_mirror row_mask:0xf bank_mask:0xf
	v_add_f32_dpp v71, v71, v71 row_mirror row_mask:0xf bank_mask:0xf
	v_add_f32_dpp v72, v72, v72 row_mirror row_mask:0xf bank_mask:0xf
	v_add_f32_dpp v73, v73, v73 row_mirror row_mask:0xf bank_mask:0xf
	v_mov_b32_e32 v74, v70
	v_mov_b32_e32 v75, v71
	v_mov_b32_e32 v76, v72
	v_mov_b32_e32 v77, v73
	v_permlane16_swap_b32_e32 v70, v74
	v_permlane16_swap_b32_e32 v71, v75
	v_permlane16_swap_b32_e32 v72, v76
	v_permlane16_swap_b32_e32 v73, v77
	v_add_f32_e32 v70, v70, v74
	v_add_f32_e32 v71, v71, v75
	v_add_f32_e32 v72, v72, v76
	v_add_f32_e32 v73, v73, v77
	v_fmamk_f32 v70, v70, 0x3c000000, v192
	v_fmamk_f32 v71, v71, 0x3c000000, v192
	v_fmamk_f32 v72, v72, 0x3c000000, v192
	v_fmamk_f32 v73, v73, 0x3c000000, v192
	v_rsq_f32_e32 v70, v70
	v_rsq_f32_e32 v71, v71
	v_rsq_f32_e32 v72, v72
	v_rsq_f32_e32 v73, v73
	s_nop 0
	v_pk_mul_f32 v[58:59], v[58:59], v[70:71]
	v_pk_mul_f32 v[42:43], v[42:43], v[70:71]
	v_pk_mul_f32 v[26:27], v[26:27], v[70:71]
	v_pk_mul_f32 v[10:11], v[10:11], v[70:71]
	v_pk_mul_f32 v[60:61], v[60:61], v[72:73]
	v_pk_mul_f32 v[44:45], v[44:45], v[72:73]
	v_pk_mul_f32 v[28:29], v[28:29], v[72:73]
	v_pk_mul_f32 v[12:13], v[12:13], v[72:73]
	s_nop 0
	v_mov_b32_dpp v74, v58 quad_perm:[1,0,3,2] row_mask:0xf bank_mask:0xf
	v_mov_b32_dpp v75, v42 quad_perm:[1,0,3,2] row_mask:0xf bank_mask:0xf
	v_mov_b32_dpp v76, v26 quad_perm:[1,0,3,2] row_mask:0xf bank_mask:0xf
	v_mov_b32_dpp v77, v10 quad_perm:[1,0,3,2] row_mask:0xf bank_mask:0xf
	v_cvt_pk_bf16_f32 v58, v58, v74
	v_cvt_pk_bf16_f32 v42, v42, v75
	v_cvt_pk_bf16_f32 v26, v26, v76
	v_cvt_pk_bf16_f32 v10, v10, v77
	v_mov_b32_dpp v74, v59 quad_perm:[1,0,3,2] row_mask:0xf bank_mask:0xf
	v_mov_b32_dpp v75, v43 quad_perm:[1,0,3,2] row_mask:0xf bank_mask:0xf
	v_mov_b32_dpp v76, v27 quad_perm:[1,0,3,2] row_mask:0xf bank_mask:0xf
	v_mov_b32_dpp v77, v11 quad_perm:[1,0,3,2] row_mask:0xf bank_mask:0xf
	v_cvt_pk_bf16_f32 v59, v59, v74
	v_cvt_pk_bf16_f32 v43, v43, v75
	v_cvt_pk_bf16_f32 v27, v27, v76
	v_cvt_pk_bf16_f32 v11, v11, v77
	v_mov_b32_dpp v74, v60 quad_perm:[1,0,3,2] row_mask:0xf bank_mask:0xf
	v_mov_b32_dpp v75, v44 quad_perm:[1,0,3,2] row_mask:0xf bank_mask:0xf
	v_mov_b32_dpp v76, v28 quad_perm:[1,0,3,2] row_mask:0xf bank_mask:0xf
	v_mov_b32_dpp v77, v12 quad_perm:[1,0,3,2] row_mask:0xf bank_mask:0xf
	v_cvt_pk_bf16_f32 v60, v60, v74
	v_cvt_pk_bf16_f32 v44, v44, v75
	v_cvt_pk_bf16_f32 v28, v28, v76
	v_cvt_pk_bf16_f32 v12, v12, v77
	v_mov_b32_dpp v74, v61 quad_perm:[1,0,3,2] row_mask:0xf bank_mask:0xf
	v_mov_b32_dpp v75, v45 quad_perm:[1,0,3,2] row_mask:0xf bank_mask:0xf
	v_mov_b32_dpp v76, v29 quad_perm:[1,0,3,2] row_mask:0xf bank_mask:0xf
	v_mov_b32_dpp v77, v13 quad_perm:[1,0,3,2] row_mask:0xf bank_mask:0xf
	v_cvt_pk_bf16_f32 v61, v61, v74
	v_cvt_pk_bf16_f32 v45, v45, v75
	v_cvt_pk_bf16_f32 v29, v29, v76
	v_cvt_pk_bf16_f32 v13, v13, v77
	ds_read_b32 v66, v218 offset:96
	ds_read_b32 v67, v218 offset:100
	ds_read_b32 v68, v218 offset:104
	ds_read_b32 v69, v218 offset:108
	s_waitcnt lgkmcnt(0)
; __device__ __forceinline__ unsigned cvt_pk_bf16(float lo, float hi) { unsigned r; asm volatile("v_cvt_pk_bf16_f32 %0, %1, %2" : "=v"(r) : "v"(lo), "v"(hi)); return r; }
; __device__ __forceinline__ int crow(int r, int hi) { return (r & 3) + 8 * (r >> 2) + 4 * hi; }
; __device__ __forceinline__ void block(const BlockRef& cur, const int j0, const int NT, const int split, const SplitRef sp, lptr lds, int tid) {
;     ...
;     if (hi == 0) li_l[r32] = l_reg; asm volatile("s_waitcnt lgkmcnt(0)" ::: "memory");
;     bf16_t* Ow = cur.O + (size_t)(wid * QBLK) * DM;
; #pragma unroll
;     for (int r = 0; r < 16; ++r) { const int orow = crow(r, hi); const float rli = __builtin_amdgcn_rcpf(li_l[orow]);
;         float v0 = o[0][r] * rli, v1 = o[1][r] * rli, v2 = o[2][r] * rli, v3 = o[3][r] * rli;
;         float ss = (v0 * v0 + v1 * v1) + (v2 * v2 + v3 * v3);
;         ss += __shfl_xor(ss, 1); ss += __shfl_xor(ss, 2); ss += __shfl_xor(ss, 4); ss += __shfl_xor(ss, 8); ss += __shfl_xor(ss, 16);
;         const float rs = rsqrtf(ss * (1.0f / 128.0f) + EPS);
;         v0 *= rs; v1 *= rs; v2 *= rs; v3 *= rs;
;         const float n0 = __shfl_xor(v0, 1), n1 = __shfl_xor(v1, 1), n2 = __shfl_xor(v2, 1), n3 = __shfl_xor(v3, 1);
;         if ((r32 & 1) == 0) { bf16_t* op = Ow + (size_t)orow * DM + r32;
;             *(unsigned*)(op) = cvt_pk_bf16(v0, n0); *(unsigned*)(op + 32) = cvt_pk_bf16(v1, n1); *(unsigned*)(op + 64) = cvt_pk_bf16(v2, n2); *(unsigned*)(op + 96) = cvt_pk_bf16(v3, n3); } }
	v_rcp_f32_e32 v66, v66
	v_rcp_f32_e32 v67, v67
	v_rcp_f32_e32 v68, v68
	v_rcp_f32_e32 v69, v69
	v_pk_mul_f32 v[62:63], v[62:63], v[66:67]
	v_pk_mul_f32 v[46:47], v[46:47], v[66:67]
	v_pk_mul_f32 v[30:31], v[30:31], v[66:67]
	v_pk_mul_f32 v[14:15], v[14:15], v[66:67]
	v_pk_mul_f32 v[64:65], v[64:65], v[68:69]
	v_pk_mul_f32 v[48:49], v[48:49], v[68:69]
	v_pk_mul_f32 v[32:33], v[32:33], v[68:69]
	v_pk_mul_f32 v[16:17], v[16:17], v[68:69]
	v_pk_mul_f32 v[70:71], v[62:63], v[62:63]
	v_pk_mul_f32 v[72:73], v[64:65], v[64:65]
	v_pk_fma_f32 v[70:71], v[46:47], v[46:47], v[70:71]
	v_pk_fma_f32 v[72:73], v[48:49], v[48:49], v[72:73]
	v_pk_fma_f32 v[70:71], v[30:31], v[30:31], v[70:71]
	v_pk_fma_f32 v[72:73], v[32:33], v[32:33], v[72:73]
	v_pk_fma_f32 v[70:71], v[14:15], v[14:15], v[70:71]
	v_pk_fma_f32 v[72:73], v[16:17], v[16:17], v[72:73]
	s_nop 1
	v_add_f32_dpp v70, v70, v70 quad_perm:[1,0,3,2] row_mask:0xf bank_mask:0xf
	v_add_f32_dpp v71, v71, v71 quad_perm:[1,0,3,2] row_mask:0xf bank_mask:0xf
	v_add_f32_dpp v72, v72, v72 quad_perm:[1,0,3,2] row_mask:0xf bank_mask:0xf
	v_add_f32_dpp v73, v73, v73 quad_perm:[1,0,3,2] row_mask:0xf bank_mask:0xf
	v_add_f32_dpp v70, v70, v70 quad_perm:[2,3,0,1] row_mask:0xf bank_mask:0xf
	v_add_f32_dpp v71, v71, v71 quad_perm:[2,3,0,1] row_mask:0xf bank_mask:0xf
	v_add_f32_dpp v72, v72, v72 quad_perm:[2,3,0,1] row_mask:0xf bank_mask:0xf
	v_add_f32_dpp v73, v73, v73 quad_perm:[2,3,0,1] row_mask:0xf bank_mask:0xf
	v_add_f32_dpp v70, v70, v70 row_half_mirror row_mask:0xf bank_mask:0xf
	v_add_f32_dpp v71, v71, v71 row_half_mirror row_mask:0xf bank_mask:0xf
	v_add_f32_dpp v72, v72, v72 row_half_mirror row_mask:0xf bank_mask:0xf
	v_add_f32_dpp v73, v73, v73 row_half_mirror row_mask:0xf bank_mask:0xf
	v_add_f32_dpp v70, v70, v70 row_mirror row_mask:0xf bank_mask:0xf
	v_add_f32_dpp v71, v71, v71 row_mirror row_mask:0xf bank_mask:0xf
	v_add_f32_dpp v72, v72, v72 row_mirror row_mask:0xf bank_mask:0xf
	v_add_f32_dpp v73, v73, v73 row_mirror row_mask:0xf bank_mask:0xf
	v_mov_b32_e32 v74, v70
	v_mov_b32_e32 v75, v71
	v_mov_b32_e32 v76, v72
	v_mov_b32_e32 v77, v73
	v_permlane16_swap_b32_e32 v70, v74
	v_permlane16_swap_b32_e32 v71, v75
	v_permlane16_swap_b32_e32 v72, v76
	v_permlane16_swap_b32_e32 v73, v77
	v_add_f32_e32 v70, v70, v74
	v_add_f32_e32 v71, v71, v75
	v_add_f32_e32 v72, v72, v76
	v_add_f32_e32 v73, v73, v77
	v_fmamk_f32 v70, v70, 0x3c000000, v192
	v_fmamk_f32 v71, v71, 0x3c000000, v192
	v_fmamk_f32 v72, v72, 0x3c000000, v192
	v_fmamk_f32 v73, v73, 0x3c000000, v192
	v_rsq_f32_e32 v70, v70
	v_rsq_f32_e32 v71, v71
	v_rsq_f32_e32 v72, v72
	v_rsq_f32_e32 v73, v73
	s_nop 0
	v_pk_mul_f32 v[62:63], v[62:63], v[70:71]
	v_pk_mul_f32 v[46:47], v[46:47], v[70:71]
	v_pk_mul_f32 v[30:31], v[30:31], v[70:71]
	v_pk_mul_f32 v[14:15], v[14:15], v[70:71]
	v_pk_mul_f32 v[64:65], v[64:65], v[72:73]
	v_pk_mul_f32 v[48:49], v[48:49], v[72:73]
	v_pk_mul_f32 v[32:33], v[32:33], v[72:73]
	v_pk_mul_f32 v[16:17], v[16:17], v[72:73]
	s_nop 0
	v_mov_b32_dpp v74, v62 quad_perm:[1,0,3,2] row_mask:0xf bank_mask:0xf
	v_mov_b32_dpp v75, v46 quad_perm:[1,0,3,2] row_mask:0xf bank_mask:0xf
	v_mov_b32_dpp v76, v30 quad_perm:[1,0,3,2] row_mask:0xf bank_mask:0xf
	v_mov_b32_dpp v77, v14 quad_perm:[1,0,3,2] row_mask:0xf bank_mask:0xf
	v_cvt_pk_bf16_f32 v62, v62, v74
	v_cvt_pk_bf16_f32 v46, v46, v75
	v_cvt_pk_bf16_f32 v30, v30, v76
	v_cvt_pk_bf16_f32 v14, v14, v77
	v_mov_b32_dpp v74, v63 quad_perm:[1,0,3,2] row_mask:0xf bank_mask:0xf
	v_mov_b32_dpp v75, v47 quad_perm:[1,0,3,2] row_mask:0xf bank_mask:0xf
	v_mov_b32_dpp v76, v31 quad_perm:[1,0,3,2] row_mask:0xf bank_mask:0xf
	v_mov_b32_dpp v77, v15 quad_perm:[1,0,3,2] row_mask:0xf bank_mask:0xf
	v_cvt_pk_bf16_f32 v63, v63, v74
	v_cvt_pk_bf16_f32 v47, v47, v75
	v_cvt_pk_bf16_f32 v31, v31, v76
	v_cvt_pk_bf16_f32 v15, v15, v77
	v_mov_b32_dpp v74, v64 quad_perm:[1,0,3,2] row_mask:0xf bank_mask:0xf
	v_mov_b32_dpp v75, v48 quad_perm:[1,0,3,2] row_mask:0xf bank_mask:0xf
	v_mov_b32_dpp v76, v32 quad_perm:[1,0,3,2] row_mask:0xf bank_mask:0xf
	v_mov_b32_dpp v77, v16 quad_perm:[1,0,3,2] row_mask:0xf bank_mask:0xf
	v_cvt_pk_bf16_f32 v64, v64, v74
	v_cvt_pk_bf16_f32 v48, v48, v75
; __device__ __forceinline__ unsigned cvt_pk_bf16(float lo, float hi) { unsigned r; asm volatile("v_cvt_pk_bf16_f32 %0, %1, %2" : "=v"(r) : "v"(lo), "v"(hi)); return r; }
; __device__ __forceinline__ void block(const BlockRef& cur, const int j0, const int NT, const int split, const SplitRef sp, lptr lds, int tid) {
;     ...
;         if ((r32 & 1) == 0) { bf16_t* op = Ow + (size_t)orow * DM + r32;
;             *(unsigned*)(op) = cvt_pk_bf16(v0, n0); *(unsigned*)(op + 32) = cvt_pk_bf16(v1, n1); *(unsigned*)(op + 64) = cvt_pk_bf16(v2, n2); *(unsigned*)(op + 96) = cvt_pk_bf16(v3, n3); } }
	v_cvt_pk_bf16_f32 v32, v32, v76
	v_cvt_pk_bf16_f32 v16, v16, v77
	v_mov_b32_dpp v74, v65 quad_perm:[1,0,3,2] row_mask:0xf bank_mask:0xf
	v_mov_b32_dpp v75, v49 quad_perm:[1,0,3,2] row_mask:0xf bank_mask:0xf
	v_mov_b32_dpp v76, v33 quad_perm:[1,0,3,2] row_mask:0xf bank_mask:0xf
	v_mov_b32_dpp v77, v17 quad_perm:[1,0,3,2] row_mask:0xf bank_mask:0xf
	v_cvt_pk_bf16_f32 v65, v65, v74
	v_cvt_pk_bf16_f32 v49, v49, v75
	v_cvt_pk_bf16_f32 v33, v33, v76
	v_cvt_pk_bf16_f32 v17, v17, v77
	s_and_saveexec_b64 s[0:1], vcc
	global_store_dword v162, v50, s[4:5]
	global_store_dword v162, v34, s[4:5] offset:64
	global_store_dword v162, v18, s[4:5] offset:128
	global_store_dword v162, v2, s[4:5] offset:192
	s_add_u32 s4, s4, 0x1000
	s_addc_u32 s5, s5, 0
	global_store_dword v162, v51, s[4:5]
	global_store_dword v162, v35, s[4:5] offset:64
	global_store_dword v162, v19, s[4:5] offset:128
	global_store_dword v162, v3, s[4:5] offset:192
	s_add_u32 s4, s4, 0x1000
	s_addc_u32 s5, s5, 0
	global_store_dword v162, v52, s[4:5]
	global_store_dword v162, v36, s[4:5] offset:64
	global_store_dword v162, v20, s[4:5] offset:128
	global_store_dword v162, v4, s[4:5] offset:192
	s_add_u32 s4, s4, 0x1000
	s_addc_u32 s5, s5, 0
	global_store_dword v162, v53, s[4:5]
	global_store_dword v162, v37, s[4:5] offset:64
	global_store_dword v162, v21, s[4:5] offset:128
	global_store_dword v162, v5, s[4:5] offset:192
	s_add_u32 s4, s4, 0x5000
	s_addc_u32 s5, s5, 0
	global_store_dword v162, v54, s[4:5]
	global_store_dword v162, v38, s[4:5] offset:64
	global_store_dword v162, v22, s[4:5] offset:128
	global_store_dword v162, v6, s[4:5] offset:192
	s_add_u32 s4, s4, 0x1000
	s_addc_u32 s5, s5, 0
	global_store_dword v162, v55, s[4:5]
	global_store_dword v162, v39, s[4:5] offset:64
	global_store_dword v162, v23, s[4:5] offset:128
	global_store_dword v162, v7, s[4:5] offset:192
	s_add_u32 s4, s4, 0x1000
	s_addc_u32 s5, s5, 0
	global_store_dword v162, v56, s[4:5]
	global_store_dword v162, v40, s[4:5] offset:64
	global_store_dword v162, v24, s[4:5] offset:128
	global_store_dword v162, v8, s[4:5] offset:192
	s_add_u32 s4, s4, 0x1000
	s_addc_u32 s5, s5, 0
	global_store_dword v162, v57, s[4:5]
	global_store_dword v162, v41, s[4:5] offset:64
	global_store_dword v162, v25, s[4:5] offset:128
	global_store_dword v162, v9, s[4:5] offset:192
	s_add_u32 s4, s4, 0x5000
	s_addc_u32 s5, s5, 0
	global_store_dword v162, v58, s[4:5]
	global_store_dword v162, v42, s[4:5] offset:64
	global_store_dword v162, v26, s[4:5] offset:128
	global_store_dword v162, v10, s[4:5] offset:192
	s_add_u32 s4, s4, 0x1000
	s_addc_u32 s5, s5, 0
	global_store_dword v162, v59, s[4:5]
	global_store_dword v162, v43, s[4:5] offset:64
	global_store_dword v162, v27, s[4:5] offset:128
	global_store_dword v162, v11, s[4:5] offset:192
	s_add_u32 s4, s4, 0x1000
	s_addc_u32 s5, s5, 0
	global_store_dword v162, v60, s[4:5]
	global_store_dword v162, v44, s[4:5] offset:64
	global_store_dword v162, v28, s[4:5] offset:128
	global_store_dword v162, v12, s[4:5] offset:192
	s_add_u32 s4, s4, 0x1000
	s_addc_u32 s5, s5, 0
	global_store_dword v162, v61, s[4:5]
	global_store_dword v162, v45, s[4:5] offset:64
	global_store_dword v162, v29, s[4:5] offset:128
	global_store_dword v162, v13, s[4:5] offset:192
	s_add_u32 s4, s4, 0x5000
	s_addc_u32 s5, s5, 0
	global_store_dword v162, v62, s[4:5]
	global_store_dword v162, v46, s[4:5] offset:64
	global_store_dword v162, v30, s[4:5] offset:128
	global_store_dword v162, v14, s[4:5] offset:192
	s_add_u32 s4, s4, 0x1000
	s_addc_u32 s5, s5, 0
	global_store_dword v162, v63, s[4:5]
	global_store_dword v162, v47, s[4:5] offset:64
	global_store_dword v162, v31, s[4:5] offset:128
	global_store_dword v162, v15, s[4:5] offset:192
	s_add_u32 s4, s4, 0x1000
	s_addc_u32 s5, s5, 0
	global_store_dword v162, v64, s[4:5]
	global_store_dword v162, v48, s[4:5] offset:64
	global_store_dword v162, v32, s[4:5] offset:128
	global_store_dword v162, v16, s[4:5] offset:192
	s_add_u32 s4, s4, 0x1000
	s_addc_u32 s5, s5, 0
	global_store_dword v162, v65, s[4:5]
	global_store_dword v162, v49, s[4:5] offset:64
	global_store_dword v162, v33, s[4:5] offset:128
	global_store_dword v162, v17, s[4:5] offset:192
	s_branch .LBB0_821
